# MLA trim + removed per-segment s_setprio flips in the four fp6 GEMM loops
# speedup vs baseline: 1.0116x; 1.0036x over previous
.LBB0_991:
	ds_read_b128 v[146:149], v142
	ds_read_b128 v[192:195], v142 offset:1024
	ds_read_b128 v[152:155], v142 offset:2048
	ds_read_b128 v[196:199], v142 offset:3072
	ds_read_b128 v[158:161], v143
	ds_read_b128 v[200:203], v143 offset:1024
	ds_read_b128 v[164:167], v143 offset:2048
	ds_read_b128 v[204:207], v143 offset:3072
	s_add_u32 s56, s54, 0xfffc0080
	s_addc_u32 s57, s55, -1
	s_cmp_eq_u32 s86, 12
	s_cselect_b32 s57, s4, s57
	s_cselect_b32 s56, s5, s56
	s_cselect_b32 s59, s39, s85
	s_cselect_b32 s58, s45, s84
	v_lshl_add_u64 v[150:151], s[54:55], 0, v[136:137]
	s_add_i32 m0, s29, 0xc000
	ds_read_b128 v[170:173], v144
	ds_read_b128 v[208:211], v144 offset:1024
	ds_read_b128 v[176:179], v144 offset:2048
	ds_read_b128 v[212:215], v144 offset:3072
	ds_read_b128 v[182:185], v144 offset:4096
	ds_read_b128 v[216:219], v144 offset:5120
	ds_read_b128 v[188:191], v144 offset:6144
	ds_read_b128 v[220:223], v144 offset:7168
	global_load_lds_dwordx4 v[150:151], off
	v_lshl_add_u64 v[150:151], v[150:151], 0, s[10:11]
	s_add_i32 m0, s29, 0xe000
	s_nop 0
	global_load_lds_dwordx4 v[150:151], off
	s_waitcnt vmcnt(8)
	s_waitcnt lgkmcnt(0)
	s_barrier
	s_waitcnt lgkmcnt(0)
	v_mov_b32_e32 v150, v192
	v_mov_b32_e32 v151, v193
	v_mov_b32_e32 v156, v196
	v_mov_b32_e32 v157, v197
	v_mov_b32_e32 v174, v208
	v_mov_b32_e32 v175, v209
	v_mov_b32_e32 v180, v212
	v_mov_b32_e32 v181, v213
	v_mov_b32_e32 v186, v216
	v_mov_b32_e32 v187, v217
	v_mov_b32_e32 v192, v220
	v_mov_b32_e32 v193, v221
	v_mfma_scale_f32_16x16x128_f8f6f4 v[128:131], v[146:151], v[170:175], v[128:131], v194, v210 op_sel_hi:[0,0,0] cbsz:2 blgp:2
	v_mfma_scale_f32_16x16x128_f8f6f4 v[124:127], v[152:157], v[170:175], v[124:127], v198, v210 op_sel_hi:[0,0,0] cbsz:2 blgp:2
	v_mfma_scale_f32_16x16x128_f8f6f4 v[120:123], v[146:151], v[176:181], v[120:123], v194, v214 op_sel_hi:[0,0,0] cbsz:2 blgp:2
	v_mfma_scale_f32_16x16x128_f8f6f4 v[116:119], v[152:157], v[176:181], v[116:119], v198, v214 op_sel_hi:[0,0,0] cbsz:2 blgp:2
	v_mfma_scale_f32_16x16x128_f8f6f4 v[112:115], v[146:151], v[182:187], v[112:115], v194, v218 op_sel_hi:[0,0,0] cbsz:2 blgp:2
	v_mfma_scale_f32_16x16x128_f8f6f4 v[108:111], v[152:157], v[182:187], v[108:111], v198, v218 op_sel_hi:[0,0,0] cbsz:2 blgp:2
	v_mfma_scale_f32_16x16x128_f8f6f4 v[104:107], v[146:151], v[188:193], v[104:107], v194, v222 op_sel_hi:[0,0,0] cbsz:2 blgp:2
	v_mfma_scale_f32_16x16x128_f8f6f4 v[100:103], v[152:157], v[188:193], v[100:103], v198, v222 op_sel_hi:[0,0,0] cbsz:2 blgp:2
	v_mov_b32_e32 v168, v204
	v_mov_b32_e32 v169, v205
	v_mov_b32_e32 v162, v200
	v_mov_b32_e32 v163, v201
	v_mfma_scale_f32_16x16x128_f8f6f4 v[30:33], v[164:169], v[188:193], v[30:33], v206, v222 op_sel_hi:[0,0,0] cbsz:2 blgp:2
	s_nop 0
	v_mfma_scale_f32_16x16x128_f8f6f4 v[224:227], v[158:163], v[170:175], v[2:5], v202, v210 op_sel_hi:[0,0,0] cbsz:2 blgp:2
	v_mfma_scale_f32_16x16x128_f8f6f4 v[170:173], v[164:169], v[170:175], v[6:9], v206, v210 op_sel_hi:[0,0,0] cbsz:2 blgp:2
	v_mfma_scale_f32_16x16x128_f8f6f4 v[208:211], v[158:163], v[176:181], v[10:13], v202, v214 op_sel_hi:[0,0,0] cbsz:2 blgp:2
	v_mfma_scale_f32_16x16x128_f8f6f4 v[174:177], v[164:169], v[176:181], v[14:17], v206, v214 op_sel_hi:[0,0,0] cbsz:2 blgp:2
	v_mfma_scale_f32_16x16x128_f8f6f4 v[178:181], v[158:163], v[182:187], v[18:21], v202, v218 op_sel_hi:[0,0,0] cbsz:2 blgp:2
	v_mfma_scale_f32_16x16x128_f8f6f4 v[182:185], v[164:169], v[182:187], v[22:25], v206, v218 op_sel_hi:[0,0,0] cbsz:2 blgp:2
	v_mfma_scale_f32_16x16x128_f8f6f4 v[212:215], v[158:163], v[188:193], v[26:29], v202, v222 op_sel_hi:[0,0,0] cbsz:2 blgp:2
	s_barrier
	v_lshl_add_u64 v[236:237], s[58:59], 0, v[132:133]
	s_add_i32 s58, s61, s24
	s_mov_b32 m0, s58
	ds_read_b128 v[2:5], v144 offset:16384
	ds_read_b128 v[24:27], v144 offset:17408
	ds_read_b128 v[8:11], v144 offset:18432
	ds_read_b128 v[186:189], v144 offset:19456
	ds_read_b128 v[14:17], v144 offset:20480
	ds_read_b128 v[190:193], v144 offset:21504
	ds_read_b128 v[20:23], v144 offset:22528
	ds_read_b128 v[216:219], v144 offset:23552
	global_load_lds_dwordx4 v[236:237], off
	v_lshl_add_u64 v[6:7], v[236:237], 0, s[10:11]
	s_add_i32 m0, s58, 0x2000
	s_add_i32 s58, s62, s24
	global_load_lds_dwordx4 v[6:7], off
	v_lshl_add_u64 v[6:7], v[236:237], 0, s[12:13]
	s_mov_b32 m0, s58
	v_lshl_add_u64 v[238:239], s[56:57], 0, v[134:135]
	global_load_lds_dwordx4 v[6:7], off
	v_lshl_add_u64 v[6:7], v[236:237], 0, s[14:15]
	s_add_i32 m0, s58, 0x2000
	s_nop 0
	global_load_lds_dwordx4 v[6:7], off
	s_mov_b32 m0, s29
	v_lshl_add_u64 v[6:7], v[238:239], 0, s[10:11]
	global_load_lds_dwordx4 v[238:239], off
	s_mov_b32 m0, s33
	s_nop 0
	global_load_lds_dwordx4 v[6:7], off
	s_waitcnt vmcnt(8)
	s_waitcnt lgkmcnt(0)
	s_barrier
	s_waitcnt lgkmcnt(0)
	v_mov_b32_e32 v6, v24
	v_mov_b32_e32 v7, v25
	v_mov_b32_e32 v12, v186
	v_mov_b32_e32 v13, v187
	v_mov_b32_e32 v18, v190
	v_mov_b32_e32 v19, v191
	v_mfma_scale_f32_16x16x128_f8f6f4 v[96:99], v[146:151], v[2:7], v[96:99], v194, v26 op_sel_hi:[0,0,0] cbsz:2 blgp:2
	v_mov_b32_e32 v24, v216
	v_mov_b32_e32 v25, v217
	v_mfma_scale_f32_16x16x128_f8f6f4 v[92:95], v[152:157], v[2:7], v[92:95], v198, v26 op_sel_hi:[0,0,0] cbsz:2 blgp:2
	v_mfma_scale_f32_16x16x128_f8f6f4 v[80:83], v[146:151], v[8:13], v[80:83], v194, v188 op_sel_hi:[0,0,0] cbsz:2 blgp:2
	v_mfma_scale_f32_16x16x128_f8f6f4 v[76:79], v[152:157], v[8:13], v[76:79], v198, v188 op_sel_hi:[0,0,0] cbsz:2 blgp:2
	v_mfma_scale_f32_16x16x128_f8f6f4 v[68:71], v[146:151], v[14:19], v[68:71], v194, v192 op_sel_hi:[0,0,0] cbsz:2 blgp:2
	v_mfma_scale_f32_16x16x128_f8f6f4 v[56:59], v[152:157], v[14:19], v[56:59], v198, v192 op_sel_hi:[0,0,0] cbsz:2 blgp:2
	v_mfma_scale_f32_16x16x128_f8f6f4 v[194:197], v[146:151], v[20:25], v[52:55], v194, v218 op_sel_hi:[0,0,0] cbsz:2 blgp:2
	v_mfma_scale_f32_16x16x128_f8f6f4 v[198:201], v[152:157], v[20:25], v[44:47], v198, v218 op_sel_hi:[0,0,0] cbsz:2 blgp:2
	v_mfma_scale_f32_16x16x128_f8f6f4 v[88:91], v[158:163], v[2:7], v[88:91], v202, v26 op_sel_hi:[0,0,0] cbsz:2 blgp:2
	v_mfma_scale_f32_16x16x128_f8f6f4 v[84:87], v[164:169], v[2:7], v[84:87], v206, v26 op_sel_hi:[0,0,0] cbsz:2 blgp:2
	v_mfma_scale_f32_16x16x128_f8f6f4 v[72:75], v[158:163], v[8:13], v[72:75], v202, v188 op_sel_hi:[0,0,0] cbsz:2 blgp:2
	v_mfma_scale_f32_16x16x128_f8f6f4 v[186:189], v[164:169], v[8:13], v[64:67], v206, v188 op_sel_hi:[0,0,0] cbsz:2 blgp:2
	v_mfma_scale_f32_16x16x128_f8f6f4 v[220:223], v[158:163], v[14:19], v[60:63], v202, v192 op_sel_hi:[0,0,0] cbsz:2 blgp:2
	v_mfma_scale_f32_16x16x128_f8f6f4 v[190:193], v[164:169], v[14:19], v[48:51], v206, v192 op_sel_hi:[0,0,0] cbsz:2 blgp:2
	v_mfma_scale_f32_16x16x128_f8f6f4 v[202:205], v[158:163], v[20:25], v[40:43], v202, v218 op_sel_hi:[0,0,0] cbsz:2 blgp:2
	v_mfma_scale_f32_16x16x128_f8f6f4 v[216:219], v[164:169], v[20:25], v[36:39], v206, v218 op_sel_hi:[0,0,0] cbsz:2 blgp:2
	s_barrier
	s_add_i32 s56, 0, 0x18000
	v_add_u32_e32 v2, s56, v1
	s_add_i32 s57, 0, 0x1c000
	ds_read_b128 v[36:39], v2
	ds_read_b128 v[52:55], v2 offset:1024
	ds_read_b128 v[42:45], v2 offset:2048
	ds_read_b128 v[64:67], v2 offset:3072
	v_add_u32_e32 v2, s57, v1
	ds_read_b128 v[146:149], v2
	ds_read_b128 v[228:231], v2 offset:1024
	ds_read_b128 v[152:155], v2 offset:2048
	ds_read_b128 v[232:235], v2 offset:3072
	s_mov_b32 m0, s40
	v_lshl_add_u64 v[2:3], v[238:239], 0, s[12:13]
	ds_read_b128 v[6:9], v144 offset:32768
	ds_read_b128 v[10:13], v144 offset:33792
	ds_read_b128 v[14:17], v144 offset:34816
	ds_read_b128 v[18:21], v144 offset:35840
	ds_read_b128 v[22:25], v144 offset:36864
	ds_read_b128 v[26:29], v144 offset:37888
	ds_read_b128 v[48:51], v144 offset:38912
	ds_read_b128 v[60:63], v144 offset:39936
	global_load_lds_dwordx4 v[2:3], off
	v_lshl_add_u64 v[2:3], v[238:239], 0, s[14:15]
	s_mov_b32 m0, s41
	s_nop 0
	global_load_lds_dwordx4 v[2:3], off
	s_waitcnt vmcnt(8)
	s_waitcnt lgkmcnt(0)
	s_barrier
	s_waitcnt lgkmcnt(0)
	v_mov_b32_e32 v40, v52
	v_mov_b32_e32 v41, v53
	v_mov_b32_e32 v46, v64
	v_mov_b32_e32 v47, v65
	v_mov_b32_e32 v52, v60
	v_mov_b32_e32 v53, v61
	v_mfma_scale_f32_16x16x128_f8f6f4 v[128:131], v[36:41], v[6:11], v[128:131], v54, v12 op_sel_hi:[0,0,0] cbsz:2 blgp:2
	v_mfma_scale_f32_16x16x128_f8f6f4 v[124:127], v[42:47], v[6:11], v[124:127], v66, v12 op_sel_hi:[0,0,0] cbsz:2 blgp:2
	v_mfma_scale_f32_16x16x128_f8f6f4 v[120:123], v[36:41], v[14:19], v[120:123], v54, v20 op_sel_hi:[0,0,0] cbsz:2 blgp:2
	v_mfma_scale_f32_16x16x128_f8f6f4 v[116:119], v[42:47], v[14:19], v[116:119], v66, v20 op_sel_hi:[0,0,0] cbsz:2 blgp:2
	v_mfma_scale_f32_16x16x128_f8f6f4 v[112:115], v[36:41], v[22:27], v[112:115], v54, v28 op_sel_hi:[0,0,0] cbsz:2 blgp:2
	v_mfma_scale_f32_16x16x128_f8f6f4 v[108:111], v[42:47], v[22:27], v[108:111], v66, v28 op_sel_hi:[0,0,0] cbsz:2 blgp:2
	v_mfma_scale_f32_16x16x128_f8f6f4 v[104:107], v[36:41], v[48:53], v[104:107], v54, v62 op_sel_hi:[0,0,0] cbsz:2 blgp:2
	v_mfma_scale_f32_16x16x128_f8f6f4 v[100:103], v[42:47], v[48:53], v[100:103], v66, v62 op_sel_hi:[0,0,0] cbsz:2 blgp:2
	v_mov_b32_e32 v150, v228
	v_mov_b32_e32 v151, v229
	v_mov_b32_e32 v156, v232
	v_mov_b32_e32 v157, v233
	v_mfma_scale_f32_16x16x128_f8f6f4 v[2:5], v[146:151], v[6:11], v[224:227], v230, v12 op_sel_hi:[0,0,0] cbsz:2 blgp:2
	s_nop 0
	v_mfma_scale_f32_16x16x128_f8f6f4 v[6:9], v[152:157], v[6:11], v[170:173], v234, v12 op_sel_hi:[0,0,0] cbsz:2 blgp:2
	v_mfma_scale_f32_16x16x128_f8f6f4 v[10:13], v[146:151], v[14:19], v[208:211], v230, v20 op_sel_hi:[0,0,0] cbsz:2 blgp:2
	v_mfma_scale_f32_16x16x128_f8f6f4 v[14:17], v[152:157], v[14:19], v[174:177], v234, v20 op_sel_hi:[0,0,0] cbsz:2 blgp:2
	v_mfma_scale_f32_16x16x128_f8f6f4 v[18:21], v[146:151], v[22:27], v[178:181], v230, v28 op_sel_hi:[0,0,0] cbsz:2 blgp:2
	v_mfma_scale_f32_16x16x128_f8f6f4 v[22:25], v[152:157], v[22:27], v[182:185], v234, v28 op_sel_hi:[0,0,0] cbsz:2 blgp:2
	v_mfma_scale_f32_16x16x128_f8f6f4 v[26:29], v[146:151], v[48:53], v[212:215], v230, v62 op_sel_hi:[0,0,0] cbsz:2 blgp:2
	v_mfma_scale_f32_16x16x128_f8f6f4 v[30:33], v[152:157], v[48:53], v[30:33], v234, v62 op_sel_hi:[0,0,0] cbsz:2 blgp:2
	s_barrier
	s_add_i32 s56, s56, s24
	v_lshl_add_u64 v[52:53], v[236:237], 0, s[22:23]
	s_mov_b32 m0, s56
	ds_read_b128 v[60:63], v144 offset:49152
	ds_read_b128 v[48:51], v144 offset:50176
	ds_read_b128 v[158:161], v144 offset:51200
	ds_read_b128 v[174:177], v144 offset:52224
	ds_read_b128 v[164:167], v144 offset:53248
	ds_read_b128 v[178:181], v144 offset:54272
	ds_read_b128 v[170:173], v144 offset:55296
	ds_read_b128 v[182:185], v144 offset:56320
	global_load_lds_dwordx4 v[52:53], off
	v_lshl_add_u64 v[52:53], v[236:237], 0, s[26:27]
	s_add_i32 m0, s56, 0x2000
	s_add_i32 s56, s57, s24
	global_load_lds_dwordx4 v[52:53], off
	v_lshl_add_u64 v[52:53], v[236:237], 0, s[30:31]
	s_mov_b32 m0, s56
	s_nop 0
	global_load_lds_dwordx4 v[52:53], off
	v_lshl_add_u64 v[52:53], v[236:237], 0, s[34:35]
	s_add_i32 m0, s56, 0x2000
	s_nop 0
	global_load_lds_dwordx4 v[52:53], off
	v_lshl_add_u64 v[52:53], v[238:239], 0, s[22:23]
	s_mov_b32 m0, s43
	s_nop 0
	global_load_lds_dwordx4 v[52:53], off
	v_lshl_add_u64 v[52:53], v[238:239], 0, s[26:27]
	s_mov_b32 m0, s50
	s_nop 0
	global_load_lds_dwordx4 v[52:53], off
	s_waitcnt vmcnt(8)
	s_waitcnt lgkmcnt(0)
	s_barrier
	s_waitcnt lgkmcnt(0)
	v_mov_b32_e32 v64, v48
	v_mov_b32_e32 v65, v49
	v_mov_b32_e32 v162, v174
	v_mov_b32_e32 v163, v175
	v_mov_b32_e32 v168, v178
	v_mov_b32_e32 v169, v179
	v_mov_b32_e32 v174, v182
	v_mov_b32_e32 v175, v183
	v_mfma_scale_f32_16x16x128_f8f6f4 v[96:99], v[36:41], v[60:65], v[96:99], v54, v50 op_sel_hi:[0,0,0] cbsz:2 blgp:2
	v_mfma_scale_f32_16x16x128_f8f6f4 v[92:95], v[42:47], v[60:65], v[92:95], v66, v50 op_sel_hi:[0,0,0] cbsz:2 blgp:2
	v_mfma_scale_f32_16x16x128_f8f6f4 v[80:83], v[36:41], v[158:163], v[80:83], v54, v176 op_sel_hi:[0,0,0] cbsz:2 blgp:2
	v_mfma_scale_f32_16x16x128_f8f6f4 v[76:79], v[42:47], v[158:163], v[76:79], v66, v176 op_sel_hi:[0,0,0] cbsz:2 blgp:2
	v_mfma_scale_f32_16x16x128_f8f6f4 v[68:71], v[36:41], v[164:169], v[68:71], v54, v180 op_sel_hi:[0,0,0] cbsz:2 blgp:2
	v_mfma_scale_f32_16x16x128_f8f6f4 v[56:59], v[42:47], v[164:169], v[56:59], v66, v180 op_sel_hi:[0,0,0] cbsz:2 blgp:2
	v_mfma_scale_f32_16x16x128_f8f6f4 v[52:55], v[36:41], v[170:175], v[194:197], v54, v184 op_sel_hi:[0,0,0] cbsz:2 blgp:2
	v_mfma_scale_f32_16x16x128_f8f6f4 v[44:47], v[42:47], v[170:175], v[198:201], v66, v184 op_sel_hi:[0,0,0] cbsz:2 blgp:2
	v_mfma_scale_f32_16x16x128_f8f6f4 v[88:91], v[146:151], v[60:65], v[88:91], v230, v50 op_sel_hi:[0,0,0] cbsz:2 blgp:2
	v_mfma_scale_f32_16x16x128_f8f6f4 v[84:87], v[152:157], v[60:65], v[84:87], v234, v50 op_sel_hi:[0,0,0] cbsz:2 blgp:2
	v_mfma_scale_f32_16x16x128_f8f6f4 v[72:75], v[146:151], v[158:163], v[72:75], v230, v176 op_sel_hi:[0,0,0] cbsz:2 blgp:2
	v_mfma_scale_f32_16x16x128_f8f6f4 v[64:67], v[152:157], v[158:163], v[186:189], v234, v176 op_sel_hi:[0,0,0] cbsz:2 blgp:2
	v_mfma_scale_f32_16x16x128_f8f6f4 v[60:63], v[146:151], v[164:169], v[220:223], v230, v180 op_sel_hi:[0,0,0] cbsz:2 blgp:2
	v_mfma_scale_f32_16x16x128_f8f6f4 v[48:51], v[152:157], v[164:169], v[190:193], v234, v180 op_sel_hi:[0,0,0] cbsz:2 blgp:2
	v_mfma_scale_f32_16x16x128_f8f6f4 v[40:43], v[146:151], v[170:175], v[202:205], v230, v184 op_sel_hi:[0,0,0] cbsz:2 blgp:2
	v_mfma_scale_f32_16x16x128_f8f6f4 v[36:39], v[152:157], v[170:175], v[216:219], v234, v184 op_sel_hi:[0,0,0] cbsz:2 blgp:2
	s_barrier
	s_add_i32 s86, s86, 2
	s_add_u32 s54, s54, 0x100
	s_addc_u32 s55, s55, 0
	s_add_u32 s84, s84, 0x100
	s_addc_u32 s85, s85, 0
	s_cmp_gt_u32 s86, 13
	s_cbranch_scc0 .LBB0_991
	s_setprio 0
	s_and_b64 vcc, exec, s[36:37]
	s_cbranch_vccz .LBB0_994
	s_barrier

.LBB0_1074:
	ds_read_b128 v[114:117], v176
	ds_read_b128 v[142:145], v176 offset:1024
	ds_read_b128 v[120:123], v176 offset:2048
	ds_read_b128 v[172:175], v176 offset:3072
	ds_read_b128 v[126:129], v177
	ds_read_b128 v[198:201], v177 offset:1024
	ds_read_b128 v[132:135], v177 offset:2048
	ds_read_b128 v[202:205], v177 offset:3072
	s_add_u32 s52, s48, 0xfff50080
	s_addc_u32 s53, s49, -1
	s_cmp_eq_u32 s63, 40
	s_cselect_b32 s53, s9, s53
	s_cselect_b32 s52, s8, s52
	s_cselect_b32 s55, s47, s5
	s_cselect_b32 s54, s46, s4
	v_lshl_add_u64 v[118:119], s[48:49], 0, v[166:167]
	s_add_i32 m0, s28, 0xc000
	ds_read_b128 v[138:141], v178
	ds_read_b128 v[206:209], v178 offset:1024
	ds_read_b128 v[180:183], v178 offset:2048
	ds_read_b128 v[210:213], v178 offset:3072
	ds_read_b128 v[186:189], v178 offset:4096
	ds_read_b128 v[214:217], v178 offset:5120
	ds_read_b128 v[192:195], v178 offset:6144
	ds_read_b128 v[218:221], v178 offset:7168
	global_load_lds_dwordx4 v[118:119], off
	v_lshl_add_u64 v[118:119], v[118:119], 0, s[12:13]
	s_add_i32 m0, s28, 0xe000
	s_nop 0
	global_load_lds_dwordx4 v[118:119], off
	s_waitcnt vmcnt(8)
	s_waitcnt lgkmcnt(0)
	s_barrier
	s_waitcnt lgkmcnt(0)
	v_mov_b32_e32 v118, v142
	v_mov_b32_e32 v119, v143
	v_mov_b32_e32 v124, v172
	v_mov_b32_e32 v125, v173
	v_mov_b32_e32 v142, v206
	v_mov_b32_e32 v143, v207
	v_mov_b32_e32 v184, v210
	v_mov_b32_e32 v185, v211
	v_mov_b32_e32 v190, v214
	v_mov_b32_e32 v191, v215
	v_mfma_scale_f32_16x16x128_f8f6f4 v[158:161], v[114:119], v[138:143], v[158:161], v144, v208 op_sel_hi:[0,0,0] cbsz:2 blgp:2
	v_mov_b32_e32 v196, v218
	v_mov_b32_e32 v197, v219
	v_mfma_scale_f32_16x16x128_f8f6f4 v[154:157], v[120:125], v[138:143], v[154:157], v174, v208 op_sel_hi:[0,0,0] cbsz:2 blgp:2
	v_mfma_scale_f32_16x16x128_f8f6f4 v[110:113], v[114:119], v[180:185], v[110:113], v144, v212 op_sel_hi:[0,0,0] cbsz:2 blgp:2
	v_mfma_scale_f32_16x16x128_f8f6f4 v[106:109], v[120:125], v[180:185], v[106:109], v174, v212 op_sel_hi:[0,0,0] cbsz:2 blgp:2
	v_mfma_scale_f32_16x16x128_f8f6f4 v[94:97], v[114:119], v[186:191], v[94:97], v144, v216 op_sel_hi:[0,0,0] cbsz:2 blgp:2
	v_mfma_scale_f32_16x16x128_f8f6f4 v[90:93], v[120:125], v[186:191], v[90:93], v174, v216 op_sel_hi:[0,0,0] cbsz:2 blgp:2
	v_mfma_scale_f32_16x16x128_f8f6f4 v[222:225], v[114:119], v[192:197], v[78:81], v144, v220 op_sel_hi:[0,0,0] cbsz:2 blgp:2
	v_mfma_scale_f32_16x16x128_f8f6f4 v[226:229], v[120:125], v[192:197], v[74:77], v174, v220 op_sel_hi:[0,0,0] cbsz:2 blgp:2
	v_mov_b32_e32 v130, v198
	v_mov_b32_e32 v131, v199
	v_mov_b32_e32 v136, v202
	v_mov_b32_e32 v137, v203
	v_mfma_scale_f32_16x16x128_f8f6f4 v[150:153], v[126:131], v[138:143], v[150:153], v200, v208 op_sel_hi:[0,0,0] cbsz:2 blgp:2
	v_mfma_scale_f32_16x16x128_f8f6f4 v[102:105], v[126:131], v[180:185], v[102:105], v200, v212 op_sel_hi:[0,0,0] cbsz:2 blgp:2
	v_mfma_scale_f32_16x16x128_f8f6f4 v[98:101], v[132:137], v[180:185], v[98:101], v204, v212 op_sel_hi:[0,0,0] cbsz:2 blgp:2
	v_mfma_scale_f32_16x16x128_f8f6f4 v[138:141], v[132:137], v[138:143], v[146:149], v204, v208 op_sel_hi:[0,0,0] cbsz:2 blgp:2
	v_mfma_scale_f32_16x16x128_f8f6f4 v[180:183], v[126:131], v[186:191], v[86:89], v200, v216 op_sel_hi:[0,0,0] cbsz:2 blgp:2
	v_mfma_scale_f32_16x16x128_f8f6f4 v[184:187], v[132:137], v[186:191], v[82:85], v204, v216 op_sel_hi:[0,0,0] cbsz:2 blgp:2
	v_mfma_scale_f32_16x16x128_f8f6f4 v[188:191], v[126:131], v[192:197], v[70:73], v200, v220 op_sel_hi:[0,0,0] cbsz:2 blgp:2
	v_mfma_scale_f32_16x16x128_f8f6f4 v[192:195], v[132:137], v[192:197], v[66:69], v204, v220 op_sel_hi:[0,0,0] cbsz:2 blgp:2
	s_barrier
	v_lshl_add_u64 v[250:251], s[54:55], 0, v[164:165]
	s_add_i32 s54, s64, s25
	s_mov_b32 m0, s54
	ds_read_b128 v[66:69], v178 offset:16384
	ds_read_b128 v[146:149], v178 offset:17408
	ds_read_b128 v[72:75], v178 offset:18432
	ds_read_b128 v[196:199], v178 offset:19456
	ds_read_b128 v[78:81], v178 offset:20480
	ds_read_b128 v[206:209], v178 offset:21504
	ds_read_b128 v[84:87], v178 offset:22528
	ds_read_b128 v[210:213], v178 offset:23552
	global_load_lds_dwordx4 v[250:251], off
	v_lshl_add_u64 v[70:71], v[250:251], 0, s[12:13]
	s_add_i32 m0, s54, 0x2000
	s_add_i32 s54, s65, s25
	global_load_lds_dwordx4 v[70:71], off
	v_lshl_add_u64 v[70:71], v[250:251], 0, s[14:15]
	s_mov_b32 m0, s54
	v_lshl_add_u64 v[252:253], s[52:53], 0, v[162:163]
	global_load_lds_dwordx4 v[70:71], off
	v_lshl_add_u64 v[70:71], v[250:251], 0, s[16:17]
	s_add_i32 m0, s54, 0x2000
	s_nop 0
	global_load_lds_dwordx4 v[70:71], off
	s_mov_b32 m0, s28
	v_lshl_add_u64 v[70:71], v[252:253], 0, s[12:13]
	global_load_lds_dwordx4 v[252:253], off
	s_mov_b32 m0, s29
	s_nop 0
	global_load_lds_dwordx4 v[70:71], off
	s_waitcnt vmcnt(8)
	s_waitcnt lgkmcnt(0)
	s_barrier
	s_waitcnt lgkmcnt(0)
	v_mov_b32_e32 v70, v146
	v_mov_b32_e32 v71, v147
	v_mov_b32_e32 v76, v196
	v_mov_b32_e32 v77, v197
	v_mfma_scale_f32_16x16x128_f8f6f4 v[62:65], v[114:119], v[66:71], v[62:65], v144, v148 op_sel_hi:[0,0,0] cbsz:2 blgp:2
	v_mov_b32_e32 v82, v206
	v_mov_b32_e32 v83, v207
	v_mov_b32_e32 v88, v210
	v_mfma_scale_f32_16x16x128_f8f6f4 v[58:61], v[120:125], v[66:71], v[58:61], v174, v148 op_sel_hi:[0,0,0] cbsz:2 blgp:2
	v_mov_b32_e32 v89, v211
	v_mfma_scale_f32_16x16x128_f8f6f4 v[46:49], v[114:119], v[72:77], v[46:49], v144, v198 op_sel_hi:[0,0,0] cbsz:2 blgp:2
	v_mfma_scale_f32_16x16x128_f8f6f4 v[42:45], v[120:125], v[72:77], v[42:45], v174, v198 op_sel_hi:[0,0,0] cbsz:2 blgp:2
	v_mfma_scale_f32_16x16x128_f8f6f4 v[214:217], v[114:119], v[78:83], v[30:33], v144, v208 op_sel_hi:[0,0,0] cbsz:2 blgp:2
	v_mfma_scale_f32_16x16x128_f8f6f4 v[218:221], v[120:125], v[78:83], v[26:29], v174, v208 op_sel_hi:[0,0,0] cbsz:2 blgp:2
	v_mfma_scale_f32_16x16x128_f8f6f4 v[230:233], v[114:119], v[84:89], v[14:17], v144, v212 op_sel_hi:[0,0,0] cbsz:2 blgp:2
	v_mfma_scale_f32_16x16x128_f8f6f4 v[172:175], v[120:125], v[84:89], v[10:13], v174, v212 op_sel_hi:[0,0,0] cbsz:2 blgp:2
	v_mfma_scale_f32_16x16x128_f8f6f4 v[54:57], v[126:131], v[66:71], v[54:57], v200, v148 op_sel_hi:[0,0,0] cbsz:2 blgp:2
	v_mfma_scale_f32_16x16x128_f8f6f4 v[50:53], v[132:137], v[66:71], v[50:53], v204, v148 op_sel_hi:[0,0,0] cbsz:2 blgp:2
	v_mfma_scale_f32_16x16x128_f8f6f4 v[38:41], v[126:131], v[72:77], v[38:41], v200, v198 op_sel_hi:[0,0,0] cbsz:2 blgp:2
	v_mfma_scale_f32_16x16x128_f8f6f4 v[196:199], v[132:137], v[72:77], v[34:37], v204, v198 op_sel_hi:[0,0,0] cbsz:2 blgp:2
	v_mfma_scale_f32_16x16x128_f8f6f4 v[234:237], v[126:131], v[78:83], v[22:25], v200, v208 op_sel_hi:[0,0,0] cbsz:2 blgp:2
	v_mfma_scale_f32_16x16x128_f8f6f4 v[206:209], v[132:137], v[78:83], v[18:21], v204, v208 op_sel_hi:[0,0,0] cbsz:2 blgp:2
	v_mfma_scale_f32_16x16x128_f8f6f4 v[200:203], v[126:131], v[84:89], v[6:9], v200, v212 op_sel_hi:[0,0,0] cbsz:2 blgp:2
	v_mfma_scale_f32_16x16x128_f8f6f4 v[210:213], v[132:137], v[84:89], v[2:5], v204, v212 op_sel_hi:[0,0,0] cbsz:2 blgp:2
	s_barrier
	s_add_i32 s52, 0, 0x18000
	v_add_u32_e32 v6, s52, v1
	s_add_i32 s53, 0, 0x1c000
	ds_read_b128 v[2:5], v6
	ds_read_b128 v[142:145], v6 offset:1024
	ds_read_b128 v[8:11], v6 offset:2048
	ds_read_b128 v[238:241], v6 offset:3072
	v_add_u32_e32 v6, s53, v1
	ds_read_b128 v[114:117], v6
	ds_read_b128 v[242:245], v6 offset:1024
	ds_read_b128 v[120:123], v6 offset:2048
	ds_read_b128 v[246:249], v6 offset:3072
	s_mov_b32 m0, s33
	v_lshl_add_u64 v[6:7], v[252:253], 0, s[14:15]
	ds_read_b128 v[14:17], v178 offset:32768
	ds_read_b128 v[66:69], v178 offset:33792
	ds_read_b128 v[20:23], v178 offset:34816
	ds_read_b128 v[70:73], v178 offset:35840
	ds_read_b128 v[26:29], v178 offset:36864
	ds_read_b128 v[80:83], v178 offset:37888
	ds_read_b128 v[32:35], v178 offset:38912
	ds_read_b128 v[124:127], v178 offset:39936
	global_load_lds_dwordx4 v[6:7], off
	v_lshl_add_u64 v[6:7], v[252:253], 0, s[16:17]
	s_mov_b32 m0, s40
	s_nop 0
	global_load_lds_dwordx4 v[6:7], off
	s_waitcnt vmcnt(8)
	s_waitcnt lgkmcnt(0)
	s_barrier
	s_waitcnt lgkmcnt(0)
	v_mov_b32_e32 v6, v142
	v_mov_b32_e32 v7, v143
	v_mov_b32_e32 v12, v238
	v_mov_b32_e32 v13, v239
	v_mov_b32_e32 v18, v66
	v_mov_b32_e32 v19, v67
	v_mov_b32_e32 v24, v70
	v_mov_b32_e32 v25, v71
	v_mov_b32_e32 v30, v80
	v_mov_b32_e32 v31, v81
	v_mov_b32_e32 v36, v124
	v_mov_b32_e32 v37, v125
	v_mfma_scale_f32_16x16x128_f8f6f4 v[158:161], v[2:7], v[14:19], v[158:161], v144, v68 op_sel_hi:[0,0,0] cbsz:2 blgp:2
	v_mfma_scale_f32_16x16x128_f8f6f4 v[154:157], v[8:13], v[14:19], v[154:157], v240, v68 op_sel_hi:[0,0,0] cbsz:2 blgp:2
	v_mfma_scale_f32_16x16x128_f8f6f4 v[110:113], v[2:7], v[20:25], v[110:113], v144, v72 op_sel_hi:[0,0,0] cbsz:2 blgp:2
	v_mfma_scale_f32_16x16x128_f8f6f4 v[106:109], v[8:13], v[20:25], v[106:109], v240, v72 op_sel_hi:[0,0,0] cbsz:2 blgp:2
	v_mfma_scale_f32_16x16x128_f8f6f4 v[94:97], v[2:7], v[26:31], v[94:97], v144, v82 op_sel_hi:[0,0,0] cbsz:2 blgp:2
	v_mfma_scale_f32_16x16x128_f8f6f4 v[90:93], v[8:13], v[26:31], v[90:93], v240, v82 op_sel_hi:[0,0,0] cbsz:2 blgp:2
	v_mfma_scale_f32_16x16x128_f8f6f4 v[78:81], v[2:7], v[32:37], v[222:225], v144, v126 op_sel_hi:[0,0,0] cbsz:2 blgp:2
	v_mfma_scale_f32_16x16x128_f8f6f4 v[74:77], v[8:13], v[32:37], v[226:229], v240, v126 op_sel_hi:[0,0,0] cbsz:2 blgp:2
	v_mov_b32_e32 v118, v242
	v_mov_b32_e32 v119, v243
	v_mov_b32_e32 v124, v246
	v_mov_b32_e32 v125, v247
	v_mfma_scale_f32_16x16x128_f8f6f4 v[150:153], v[114:119], v[14:19], v[150:153], v244, v68 op_sel_hi:[0,0,0] cbsz:2 blgp:2
	s_nop 0
	v_mfma_scale_f32_16x16x128_f8f6f4 v[146:149], v[120:125], v[14:19], v[138:141], v248, v68 op_sel_hi:[0,0,0] cbsz:2 blgp:2
	v_mfma_scale_f32_16x16x128_f8f6f4 v[102:105], v[114:119], v[20:25], v[102:105], v244, v72 op_sel_hi:[0,0,0] cbsz:2 blgp:2
	v_mfma_scale_f32_16x16x128_f8f6f4 v[98:101], v[120:125], v[20:25], v[98:101], v248, v72 op_sel_hi:[0,0,0] cbsz:2 blgp:2
	v_mfma_scale_f32_16x16x128_f8f6f4 v[86:89], v[114:119], v[26:31], v[180:183], v244, v82 op_sel_hi:[0,0,0] cbsz:2 blgp:2
	v_mfma_scale_f32_16x16x128_f8f6f4 v[82:85], v[120:125], v[26:31], v[184:187], v248, v82 op_sel_hi:[0,0,0] cbsz:2 blgp:2
	v_mfma_scale_f32_16x16x128_f8f6f4 v[70:73], v[114:119], v[32:37], v[188:191], v244, v126 op_sel_hi:[0,0,0] cbsz:2 blgp:2
	v_mfma_scale_f32_16x16x128_f8f6f4 v[66:69], v[120:125], v[32:37], v[192:195], v248, v126 op_sel_hi:[0,0,0] cbsz:2 blgp:2
	s_barrier
	s_add_i32 s52, s52, s25
	v_lshl_add_u64 v[14:15], v[250:251], 0, s[26:27]
	s_mov_b32 m0, s52
	ds_read_b128 v[18:21], v178 offset:49152
	ds_read_b128 v[22:25], v178 offset:50176
	ds_read_b128 v[126:129], v178 offset:51200
	ds_read_b128 v[32:35], v178 offset:52224
	ds_read_b128 v[132:135], v178 offset:53248
	ds_read_b128 v[180:183], v178 offset:54272
	ds_read_b128 v[138:141], v178 offset:55296
	ds_read_b128 v[184:187], v178 offset:56320
	global_load_lds_dwordx4 v[14:15], off
	v_lshl_add_u64 v[14:15], v[250:251], 0, s[30:31]
	s_add_i32 m0, s52, 0x2000
	s_add_i32 s52, s53, s25
	global_load_lds_dwordx4 v[14:15], off
	v_lshl_add_u64 v[14:15], v[250:251], 0, s[34:35]
	s_mov_b32 m0, s52
	s_nop 0
	global_load_lds_dwordx4 v[14:15], off
	v_lshl_add_u64 v[14:15], v[250:251], 0, s[36:37]
	s_add_i32 m0, s52, 0x2000
	s_nop 0
	global_load_lds_dwordx4 v[14:15], off
	v_lshl_add_u64 v[14:15], v[252:253], 0, s[26:27]
	s_mov_b32 m0, s43
	s_nop 0
	global_load_lds_dwordx4 v[14:15], off
	v_lshl_add_u64 v[14:15], v[252:253], 0, s[30:31]
	s_mov_b32 m0, s45
	s_nop 0
	global_load_lds_dwordx4 v[14:15], off
	s_waitcnt vmcnt(8)
	s_waitcnt lgkmcnt(0)
	s_barrier
	s_waitcnt lgkmcnt(0)
	v_mov_b32_e32 v130, v32
	v_mov_b32_e32 v131, v33
	v_mov_b32_e32 v136, v180
	v_mov_b32_e32 v137, v181
	v_mov_b32_e32 v142, v184
	v_mov_b32_e32 v143, v185
	v_mfma_scale_f32_16x16x128_f8f6f4 v[62:65], v[2:7], v[18:23], v[62:65], v144, v24 op_sel_hi:[0,0,0] cbsz:2 blgp:2
	v_mfma_scale_f32_16x16x128_f8f6f4 v[58:61], v[8:13], v[18:23], v[58:61], v240, v24 op_sel_hi:[0,0,0] cbsz:2 blgp:2
	v_mfma_scale_f32_16x16x128_f8f6f4 v[46:49], v[2:7], v[126:131], v[46:49], v144, v34 op_sel_hi:[0,0,0] cbsz:2 blgp:2
	v_mfma_scale_f32_16x16x128_f8f6f4 v[42:45], v[8:13], v[126:131], v[42:45], v240, v34 op_sel_hi:[0,0,0] cbsz:2 blgp:2
	v_mfma_scale_f32_16x16x128_f8f6f4 v[30:33], v[2:7], v[132:137], v[214:217], v144, v182 op_sel_hi:[0,0,0] cbsz:2 blgp:2
	v_mfma_scale_f32_16x16x128_f8f6f4 v[26:29], v[8:13], v[132:137], v[218:221], v240, v182 op_sel_hi:[0,0,0] cbsz:2 blgp:2
	v_mfma_scale_f32_16x16x128_f8f6f4 v[14:17], v[2:7], v[138:143], v[230:233], v144, v186 op_sel_hi:[0,0,0] cbsz:2 blgp:2
	v_mfma_scale_f32_16x16x128_f8f6f4 v[10:13], v[8:13], v[138:143], v[172:175], v240, v186 op_sel_hi:[0,0,0] cbsz:2 blgp:2
	v_mfma_scale_f32_16x16x128_f8f6f4 v[54:57], v[114:119], v[18:23], v[54:57], v244, v24 op_sel_hi:[0,0,0] cbsz:2 blgp:2
	v_mfma_scale_f32_16x16x128_f8f6f4 v[50:53], v[120:125], v[18:23], v[50:53], v248, v24 op_sel_hi:[0,0,0] cbsz:2 blgp:2
	v_mfma_scale_f32_16x16x128_f8f6f4 v[38:41], v[114:119], v[126:131], v[38:41], v244, v34 op_sel_hi:[0,0,0] cbsz:2 blgp:2
	v_mfma_scale_f32_16x16x128_f8f6f4 v[34:37], v[120:125], v[126:131], v[196:199], v248, v34 op_sel_hi:[0,0,0] cbsz:2 blgp:2
	v_mfma_scale_f32_16x16x128_f8f6f4 v[22:25], v[114:119], v[132:137], v[234:237], v244, v182 op_sel_hi:[0,0,0] cbsz:2 blgp:2
	v_mfma_scale_f32_16x16x128_f8f6f4 v[18:21], v[120:125], v[132:137], v[206:209], v248, v182 op_sel_hi:[0,0,0] cbsz:2 blgp:2
	v_mfma_scale_f32_16x16x128_f8f6f4 v[6:9], v[114:119], v[138:143], v[200:203], v244, v186 op_sel_hi:[0,0,0] cbsz:2 blgp:2
	v_mfma_scale_f32_16x16x128_f8f6f4 v[2:5], v[120:125], v[138:143], v[210:213], v248, v186 op_sel_hi:[0,0,0] cbsz:2 blgp:2
	s_barrier
	s_add_i32 s63, s63, 2
	s_add_u32 s48, s48, 0x100
	s_addc_u32 s49, s49, 0
	s_add_u32 s4, s4, 0x100
	s_addc_u32 s5, s5, 0
	s_cmp_gt_u32 s63, 41
	s_cbranch_scc0 .LBB0_1074
	s_setprio 0
	s_and_b64 vcc, exec, s[38:39]
	s_cbranch_vccz .LBB0_1077
	s_barrier

.LBB0_2187:
	ds_read_b128 v[142:145], v138
	ds_read_b128 v[188:191], v138 offset:1024
	ds_read_b128 v[148:151], v138 offset:2048
	ds_read_b128 v[192:195], v138 offset:3072
	ds_read_b128 v[154:157], v139
	ds_read_b128 v[196:199], v139 offset:1024
	ds_read_b128 v[160:163], v139 offset:2048
	ds_read_b128 v[200:203], v139 offset:3072
	s_add_u32 s50, s48, 0xfffc0080
	s_addc_u32 s51, s49, -1
	s_cmp_eq_u32 s76, 12
	s_cselect_b32 s51, s35, s51
	s_cselect_b32 s50, s47, s50
	s_cselect_b32 s53, s37, s67
	s_cselect_b32 s52, s65, s66
	v_lshl_add_u64 v[146:147], s[48:49], 0, v[136:137]
	s_add_i32 m0, s33, 0xc000
	ds_read_b128 v[166:169], v140
	ds_read_b128 v[204:207], v140 offset:1024
	ds_read_b128 v[172:175], v140 offset:2048
	ds_read_b128 v[208:211], v140 offset:3072
	ds_read_b128 v[178:181], v140 offset:4096
	ds_read_b128 v[212:215], v140 offset:5120
	ds_read_b128 v[184:187], v140 offset:6144
	ds_read_b128 v[216:219], v140 offset:7168
	global_load_lds_dwordx4 v[146:147], off
	v_lshl_add_u64 v[146:147], v[146:147], 0, s[6:7]
	s_add_i32 m0, s33, 0xe000
	s_nop 0
	global_load_lds_dwordx4 v[146:147], off
	s_waitcnt vmcnt(8)
	s_waitcnt lgkmcnt(0)
	s_barrier
	s_waitcnt lgkmcnt(0)
	v_mov_b32_e32 v146, v188
	v_mov_b32_e32 v147, v189
	v_mov_b32_e32 v152, v192
	v_mov_b32_e32 v153, v193
	v_mov_b32_e32 v170, v204
	v_mov_b32_e32 v171, v205
	v_mov_b32_e32 v176, v208
	v_mov_b32_e32 v177, v209
	v_mov_b32_e32 v182, v212
	v_mov_b32_e32 v183, v213
	v_mov_b32_e32 v188, v216
	v_mov_b32_e32 v189, v217
	v_mfma_scale_f32_16x16x128_f8f6f4 v[128:131], v[142:147], v[166:171], v[128:131], v190, v206 op_sel_hi:[0,0,0] cbsz:2 blgp:2
	v_mfma_scale_f32_16x16x128_f8f6f4 v[124:127], v[148:153], v[166:171], v[124:127], v194, v206 op_sel_hi:[0,0,0] cbsz:2 blgp:2
	v_mfma_scale_f32_16x16x128_f8f6f4 v[120:123], v[142:147], v[172:177], v[120:123], v190, v210 op_sel_hi:[0,0,0] cbsz:2 blgp:2
	v_mfma_scale_f32_16x16x128_f8f6f4 v[116:119], v[148:153], v[172:177], v[116:119], v194, v210 op_sel_hi:[0,0,0] cbsz:2 blgp:2
	v_mfma_scale_f32_16x16x128_f8f6f4 v[112:115], v[142:147], v[178:183], v[112:115], v190, v214 op_sel_hi:[0,0,0] cbsz:2 blgp:2
	v_mfma_scale_f32_16x16x128_f8f6f4 v[108:111], v[148:153], v[178:183], v[108:111], v194, v214 op_sel_hi:[0,0,0] cbsz:2 blgp:2
	v_mfma_scale_f32_16x16x128_f8f6f4 v[104:107], v[142:147], v[184:189], v[104:107], v190, v218 op_sel_hi:[0,0,0] cbsz:2 blgp:2
	v_mfma_scale_f32_16x16x128_f8f6f4 v[100:103], v[148:153], v[184:189], v[100:103], v194, v218 op_sel_hi:[0,0,0] cbsz:2 blgp:2
	v_mov_b32_e32 v164, v200
	v_mov_b32_e32 v165, v201
	v_mov_b32_e32 v158, v196
	v_mov_b32_e32 v159, v197
	v_mfma_scale_f32_16x16x128_f8f6f4 v[30:33], v[160:165], v[184:189], v[30:33], v202, v218 op_sel_hi:[0,0,0] cbsz:2 blgp:2
	s_nop 0
	v_mfma_scale_f32_16x16x128_f8f6f4 v[220:223], v[154:159], v[166:171], v[2:5], v198, v206 op_sel_hi:[0,0,0] cbsz:2 blgp:2
	v_mfma_scale_f32_16x16x128_f8f6f4 v[166:169], v[160:165], v[166:171], v[6:9], v202, v206 op_sel_hi:[0,0,0] cbsz:2 blgp:2
	v_mfma_scale_f32_16x16x128_f8f6f4 v[204:207], v[154:159], v[172:177], v[10:13], v198, v210 op_sel_hi:[0,0,0] cbsz:2 blgp:2
	v_mfma_scale_f32_16x16x128_f8f6f4 v[170:173], v[160:165], v[172:177], v[14:17], v202, v210 op_sel_hi:[0,0,0] cbsz:2 blgp:2
	v_mfma_scale_f32_16x16x128_f8f6f4 v[174:177], v[154:159], v[178:183], v[18:21], v198, v214 op_sel_hi:[0,0,0] cbsz:2 blgp:2
	v_mfma_scale_f32_16x16x128_f8f6f4 v[178:181], v[160:165], v[178:183], v[22:25], v202, v214 op_sel_hi:[0,0,0] cbsz:2 blgp:2
	v_mfma_scale_f32_16x16x128_f8f6f4 v[208:211], v[154:159], v[184:189], v[26:29], v198, v218 op_sel_hi:[0,0,0] cbsz:2 blgp:2
	s_barrier
	v_lshl_add_u64 v[232:233], s[52:53], 0, v[132:133]
	s_add_i32 s52, s57, s29
	s_mov_b32 m0, s52
	ds_read_b128 v[2:5], v140 offset:16384
	ds_read_b128 v[24:27], v140 offset:17408
	ds_read_b128 v[8:11], v140 offset:18432
	ds_read_b128 v[182:185], v140 offset:19456
	ds_read_b128 v[14:17], v140 offset:20480
	ds_read_b128 v[186:189], v140 offset:21504
	ds_read_b128 v[20:23], v140 offset:22528
	ds_read_b128 v[212:215], v140 offset:23552
	global_load_lds_dwordx4 v[232:233], off
	v_lshl_add_u64 v[6:7], v[232:233], 0, s[6:7]
	s_add_i32 m0, s52, 0x2000
	s_add_i32 s52, s58, s29
	global_load_lds_dwordx4 v[6:7], off
	v_lshl_add_u64 v[6:7], v[232:233], 0, s[8:9]
	s_mov_b32 m0, s52
	v_lshl_add_u64 v[234:235], s[50:51], 0, v[134:135]
	global_load_lds_dwordx4 v[6:7], off
	v_lshl_add_u64 v[6:7], v[232:233], 0, s[10:11]
	s_add_i32 m0, s52, 0x2000
	s_nop 0
	global_load_lds_dwordx4 v[6:7], off
	s_mov_b32 m0, s33
	v_lshl_add_u64 v[6:7], v[234:235], 0, s[6:7]
	global_load_lds_dwordx4 v[234:235], off
	s_mov_b32 m0, s40
	s_nop 0
	global_load_lds_dwordx4 v[6:7], off
	s_waitcnt vmcnt(8)
	s_waitcnt lgkmcnt(0)
	s_barrier
	s_waitcnt lgkmcnt(0)
	v_mov_b32_e32 v6, v24
	v_mov_b32_e32 v7, v25
	v_mov_b32_e32 v12, v182
	v_mov_b32_e32 v13, v183
	v_mov_b32_e32 v18, v186
	v_mov_b32_e32 v19, v187
	v_mfma_scale_f32_16x16x128_f8f6f4 v[96:99], v[142:147], v[2:7], v[96:99], v190, v26 op_sel_hi:[0,0,0] cbsz:2 blgp:2
	v_mov_b32_e32 v24, v212
	v_mov_b32_e32 v25, v213
	v_mfma_scale_f32_16x16x128_f8f6f4 v[92:95], v[148:153], v[2:7], v[92:95], v194, v26 op_sel_hi:[0,0,0] cbsz:2 blgp:2
	v_mfma_scale_f32_16x16x128_f8f6f4 v[80:83], v[142:147], v[8:13], v[80:83], v190, v184 op_sel_hi:[0,0,0] cbsz:2 blgp:2
	v_mfma_scale_f32_16x16x128_f8f6f4 v[76:79], v[148:153], v[8:13], v[76:79], v194, v184 op_sel_hi:[0,0,0] cbsz:2 blgp:2
	v_mfma_scale_f32_16x16x128_f8f6f4 v[68:71], v[142:147], v[14:19], v[68:71], v190, v188 op_sel_hi:[0,0,0] cbsz:2 blgp:2
	v_mfma_scale_f32_16x16x128_f8f6f4 v[56:59], v[148:153], v[14:19], v[56:59], v194, v188 op_sel_hi:[0,0,0] cbsz:2 blgp:2
	v_mfma_scale_f32_16x16x128_f8f6f4 v[190:193], v[142:147], v[20:25], v[52:55], v190, v214 op_sel_hi:[0,0,0] cbsz:2 blgp:2
	v_mfma_scale_f32_16x16x128_f8f6f4 v[194:197], v[148:153], v[20:25], v[44:47], v194, v214 op_sel_hi:[0,0,0] cbsz:2 blgp:2
	v_mfma_scale_f32_16x16x128_f8f6f4 v[88:91], v[154:159], v[2:7], v[88:91], v198, v26 op_sel_hi:[0,0,0] cbsz:2 blgp:2
	v_mfma_scale_f32_16x16x128_f8f6f4 v[84:87], v[160:165], v[2:7], v[84:87], v202, v26 op_sel_hi:[0,0,0] cbsz:2 blgp:2
	v_mfma_scale_f32_16x16x128_f8f6f4 v[72:75], v[154:159], v[8:13], v[72:75], v198, v184 op_sel_hi:[0,0,0] cbsz:2 blgp:2
	v_mfma_scale_f32_16x16x128_f8f6f4 v[182:185], v[160:165], v[8:13], v[64:67], v202, v184 op_sel_hi:[0,0,0] cbsz:2 blgp:2
	v_mfma_scale_f32_16x16x128_f8f6f4 v[216:219], v[154:159], v[14:19], v[60:63], v198, v188 op_sel_hi:[0,0,0] cbsz:2 blgp:2
	v_mfma_scale_f32_16x16x128_f8f6f4 v[186:189], v[160:165], v[14:19], v[48:51], v202, v188 op_sel_hi:[0,0,0] cbsz:2 blgp:2
	v_mfma_scale_f32_16x16x128_f8f6f4 v[198:201], v[154:159], v[20:25], v[40:43], v198, v214 op_sel_hi:[0,0,0] cbsz:2 blgp:2
	v_mfma_scale_f32_16x16x128_f8f6f4 v[212:215], v[160:165], v[20:25], v[36:39], v202, v214 op_sel_hi:[0,0,0] cbsz:2 blgp:2
	s_barrier
	s_add_i32 s50, 0, 0x18000
	v_add_u32_e32 v2, s50, v1
	s_add_i32 s51, 0, 0x1c000
	ds_read_b128 v[36:39], v2
	ds_read_b128 v[52:55], v2 offset:1024
	ds_read_b128 v[42:45], v2 offset:2048
	ds_read_b128 v[64:67], v2 offset:3072
	v_add_u32_e32 v2, s51, v1
	ds_read_b128 v[142:145], v2
	ds_read_b128 v[224:227], v2 offset:1024
	ds_read_b128 v[148:151], v2 offset:2048
	ds_read_b128 v[228:231], v2 offset:3072
	s_mov_b32 m0, s41
	v_lshl_add_u64 v[2:3], v[234:235], 0, s[8:9]
	ds_read_b128 v[6:9], v140 offset:32768
	ds_read_b128 v[10:13], v140 offset:33792
	ds_read_b128 v[14:17], v140 offset:34816
	ds_read_b128 v[18:21], v140 offset:35840
	ds_read_b128 v[22:25], v140 offset:36864
	ds_read_b128 v[26:29], v140 offset:37888
	ds_read_b128 v[48:51], v140 offset:38912
	ds_read_b128 v[60:63], v140 offset:39936
	global_load_lds_dwordx4 v[2:3], off
	v_lshl_add_u64 v[2:3], v[234:235], 0, s[10:11]
	s_mov_b32 m0, s42
	s_nop 0
	global_load_lds_dwordx4 v[2:3], off
	s_waitcnt vmcnt(8)
	s_waitcnt lgkmcnt(0)
	s_barrier
	s_waitcnt lgkmcnt(0)
	v_mov_b32_e32 v40, v52
	v_mov_b32_e32 v41, v53
	v_mov_b32_e32 v46, v64
	v_mov_b32_e32 v47, v65
	v_mov_b32_e32 v52, v60
	v_mov_b32_e32 v53, v61
	v_mfma_scale_f32_16x16x128_f8f6f4 v[128:131], v[36:41], v[6:11], v[128:131], v54, v12 op_sel_hi:[0,0,0] cbsz:2 blgp:2
	v_mfma_scale_f32_16x16x128_f8f6f4 v[124:127], v[42:47], v[6:11], v[124:127], v66, v12 op_sel_hi:[0,0,0] cbsz:2 blgp:2
	v_mfma_scale_f32_16x16x128_f8f6f4 v[120:123], v[36:41], v[14:19], v[120:123], v54, v20 op_sel_hi:[0,0,0] cbsz:2 blgp:2
	v_mfma_scale_f32_16x16x128_f8f6f4 v[116:119], v[42:47], v[14:19], v[116:119], v66, v20 op_sel_hi:[0,0,0] cbsz:2 blgp:2
	v_mfma_scale_f32_16x16x128_f8f6f4 v[112:115], v[36:41], v[22:27], v[112:115], v54, v28 op_sel_hi:[0,0,0] cbsz:2 blgp:2
	v_mfma_scale_f32_16x16x128_f8f6f4 v[108:111], v[42:47], v[22:27], v[108:111], v66, v28 op_sel_hi:[0,0,0] cbsz:2 blgp:2
	v_mfma_scale_f32_16x16x128_f8f6f4 v[104:107], v[36:41], v[48:53], v[104:107], v54, v62 op_sel_hi:[0,0,0] cbsz:2 blgp:2
	v_mfma_scale_f32_16x16x128_f8f6f4 v[100:103], v[42:47], v[48:53], v[100:103], v66, v62 op_sel_hi:[0,0,0] cbsz:2 blgp:2
	v_mov_b32_e32 v146, v224
	v_mov_b32_e32 v147, v225
	v_mov_b32_e32 v152, v228
	v_mov_b32_e32 v153, v229
	v_mfma_scale_f32_16x16x128_f8f6f4 v[2:5], v[142:147], v[6:11], v[220:223], v226, v12 op_sel_hi:[0,0,0] cbsz:2 blgp:2
	s_nop 0
	v_mfma_scale_f32_16x16x128_f8f6f4 v[6:9], v[148:153], v[6:11], v[166:169], v230, v12 op_sel_hi:[0,0,0] cbsz:2 blgp:2
	v_mfma_scale_f32_16x16x128_f8f6f4 v[10:13], v[142:147], v[14:19], v[204:207], v226, v20 op_sel_hi:[0,0,0] cbsz:2 blgp:2
	v_mfma_scale_f32_16x16x128_f8f6f4 v[14:17], v[148:153], v[14:19], v[170:173], v230, v20 op_sel_hi:[0,0,0] cbsz:2 blgp:2
	v_mfma_scale_f32_16x16x128_f8f6f4 v[18:21], v[142:147], v[22:27], v[174:177], v226, v28 op_sel_hi:[0,0,0] cbsz:2 blgp:2
	v_mfma_scale_f32_16x16x128_f8f6f4 v[22:25], v[148:153], v[22:27], v[178:181], v230, v28 op_sel_hi:[0,0,0] cbsz:2 blgp:2
	v_mfma_scale_f32_16x16x128_f8f6f4 v[26:29], v[142:147], v[48:53], v[208:211], v226, v62 op_sel_hi:[0,0,0] cbsz:2 blgp:2
	v_mfma_scale_f32_16x16x128_f8f6f4 v[30:33], v[148:153], v[48:53], v[30:33], v230, v62 op_sel_hi:[0,0,0] cbsz:2 blgp:2
	s_barrier
	s_add_i32 s50, s50, s29
	v_lshl_add_u64 v[52:53], v[232:233], 0, s[20:21]
	s_mov_b32 m0, s50
	ds_read_b128 v[60:63], v140 offset:49152
	ds_read_b128 v[48:51], v140 offset:50176
	ds_read_b128 v[154:157], v140 offset:51200
	ds_read_b128 v[170:173], v140 offset:52224
	ds_read_b128 v[160:163], v140 offset:53248
	ds_read_b128 v[174:177], v140 offset:54272
	ds_read_b128 v[166:169], v140 offset:55296
	ds_read_b128 v[178:181], v140 offset:56320
	global_load_lds_dwordx4 v[52:53], off
	v_lshl_add_u64 v[52:53], v[232:233], 0, s[22:23]
	s_add_i32 m0, s50, 0x2000
	s_add_i32 s50, s51, s29
	global_load_lds_dwordx4 v[52:53], off
	v_lshl_add_u64 v[52:53], v[232:233], 0, s[24:25]
	s_mov_b32 m0, s50
	s_nop 0
	global_load_lds_dwordx4 v[52:53], off
	v_lshl_add_u64 v[52:53], v[232:233], 0, s[26:27]
	s_add_i32 m0, s50, 0x2000
	s_nop 0
	global_load_lds_dwordx4 v[52:53], off
	v_lshl_add_u64 v[52:53], v[234:235], 0, s[20:21]
	s_mov_b32 m0, s43
	s_nop 0
	global_load_lds_dwordx4 v[52:53], off
	v_lshl_add_u64 v[52:53], v[234:235], 0, s[22:23]
	s_mov_b32 m0, s54
	s_nop 0
	global_load_lds_dwordx4 v[52:53], off
	s_waitcnt vmcnt(8)
	s_waitcnt lgkmcnt(0)
	s_barrier
	s_waitcnt lgkmcnt(0)
	v_mov_b32_e32 v64, v48
	v_mov_b32_e32 v65, v49
	v_mov_b32_e32 v158, v170
	v_mov_b32_e32 v159, v171
	v_mov_b32_e32 v164, v174
	v_mov_b32_e32 v165, v175
	v_mov_b32_e32 v170, v178
	v_mov_b32_e32 v171, v179
	v_mfma_scale_f32_16x16x128_f8f6f4 v[96:99], v[36:41], v[60:65], v[96:99], v54, v50 op_sel_hi:[0,0,0] cbsz:2 blgp:2
	v_mfma_scale_f32_16x16x128_f8f6f4 v[92:95], v[42:47], v[60:65], v[92:95], v66, v50 op_sel_hi:[0,0,0] cbsz:2 blgp:2
	v_mfma_scale_f32_16x16x128_f8f6f4 v[80:83], v[36:41], v[154:159], v[80:83], v54, v172 op_sel_hi:[0,0,0] cbsz:2 blgp:2
	v_mfma_scale_f32_16x16x128_f8f6f4 v[76:79], v[42:47], v[154:159], v[76:79], v66, v172 op_sel_hi:[0,0,0] cbsz:2 blgp:2
	v_mfma_scale_f32_16x16x128_f8f6f4 v[68:71], v[36:41], v[160:165], v[68:71], v54, v176 op_sel_hi:[0,0,0] cbsz:2 blgp:2
	v_mfma_scale_f32_16x16x128_f8f6f4 v[56:59], v[42:47], v[160:165], v[56:59], v66, v176 op_sel_hi:[0,0,0] cbsz:2 blgp:2
	v_mfma_scale_f32_16x16x128_f8f6f4 v[52:55], v[36:41], v[166:171], v[190:193], v54, v180 op_sel_hi:[0,0,0] cbsz:2 blgp:2
	v_mfma_scale_f32_16x16x128_f8f6f4 v[44:47], v[42:47], v[166:171], v[194:197], v66, v180 op_sel_hi:[0,0,0] cbsz:2 blgp:2
	v_mfma_scale_f32_16x16x128_f8f6f4 v[88:91], v[142:147], v[60:65], v[88:91], v226, v50 op_sel_hi:[0,0,0] cbsz:2 blgp:2
	v_mfma_scale_f32_16x16x128_f8f6f4 v[84:87], v[148:153], v[60:65], v[84:87], v230, v50 op_sel_hi:[0,0,0] cbsz:2 blgp:2
	v_mfma_scale_f32_16x16x128_f8f6f4 v[72:75], v[142:147], v[154:159], v[72:75], v226, v172 op_sel_hi:[0,0,0] cbsz:2 blgp:2
	v_mfma_scale_f32_16x16x128_f8f6f4 v[64:67], v[148:153], v[154:159], v[182:185], v230, v172 op_sel_hi:[0,0,0] cbsz:2 blgp:2
	v_mfma_scale_f32_16x16x128_f8f6f4 v[60:63], v[142:147], v[160:165], v[216:219], v226, v176 op_sel_hi:[0,0,0] cbsz:2 blgp:2
	v_mfma_scale_f32_16x16x128_f8f6f4 v[48:51], v[148:153], v[160:165], v[186:189], v230, v176 op_sel_hi:[0,0,0] cbsz:2 blgp:2
	v_mfma_scale_f32_16x16x128_f8f6f4 v[40:43], v[142:147], v[166:171], v[198:201], v226, v180 op_sel_hi:[0,0,0] cbsz:2 blgp:2
	v_mfma_scale_f32_16x16x128_f8f6f4 v[36:39], v[148:153], v[166:171], v[212:215], v230, v180 op_sel_hi:[0,0,0] cbsz:2 blgp:2
	s_barrier
	s_add_i32 s76, s76, 2
	s_add_u32 s48, s48, 0x100
	s_addc_u32 s49, s49, 0
	s_add_u32 s66, s66, 0x100
	s_addc_u32 s67, s67, 0
	s_cmp_gt_u32 s76, 13
	s_cbranch_scc0 .LBB0_2187
	s_setprio 0
	s_and_b64 vcc, exec, s[30:31]
	s_cbranch_vccz .LBB0_2190
	s_barrier

.LBB0_2291:
	ds_read_b128 v[144:147], v140
	ds_read_b128 v[190:193], v140 offset:1024
	ds_read_b128 v[150:153], v140 offset:2048
	ds_read_b128 v[194:197], v140 offset:3072
	ds_read_b128 v[156:159], v141
	ds_read_b128 v[198:201], v141 offset:1024
	ds_read_b128 v[162:165], v141 offset:2048
	ds_read_b128 v[202:205], v141 offset:3072
	s_add_i32 s76, s46, 2
	s_add_u32 s48, s44, 0xfff20080
	s_addc_u32 s47, s45, -1
	s_cmp_eq_u32 s4, s46
	s_cselect_b32 s46, s38, s48
	s_cselect_b32 s47, s39, s47
	s_cselect_b32 s49, s7, s67
	s_cselect_b32 s48, s6, s5
	v_lshl_add_u64 v[138:139], s[44:45], 0, v[136:137]
	s_add_i32 m0, s33, 0xc000
	ds_read_b128 v[168:171], v142
	ds_read_b128 v[206:209], v142 offset:1024
	ds_read_b128 v[174:177], v142 offset:2048
	ds_read_b128 v[210:213], v142 offset:3072
	ds_read_b128 v[180:183], v142 offset:4096
	ds_read_b128 v[214:217], v142 offset:5120
	ds_read_b128 v[186:189], v142 offset:6144
	ds_read_b128 v[218:221], v142 offset:7168
	global_load_lds_dwordx4 v[138:139], off
	v_lshl_add_u64 v[138:139], v[138:139], 0, s[8:9]
	s_add_i32 m0, s33, 0xe000
	s_nop 0
	global_load_lds_dwordx4 v[138:139], off
	s_waitcnt vmcnt(8)
	s_waitcnt lgkmcnt(0)
	s_barrier
	s_waitcnt lgkmcnt(0)
	v_mov_b32_e32 v148, v190
	v_mov_b32_e32 v149, v191
	v_mov_b32_e32 v154, v194
	v_mov_b32_e32 v155, v195
	v_mov_b32_e32 v172, v206
	v_mov_b32_e32 v173, v207
	v_mov_b32_e32 v178, v210
	v_mov_b32_e32 v179, v211
	v_mov_b32_e32 v184, v214
	v_mov_b32_e32 v185, v215
	v_mfma_scale_f32_16x16x128_f8f6f4 v[126:129], v[144:149], v[168:173], v[126:129], v192, v208 op_sel_hi:[0,0,0] cbsz:2 blgp:2
	v_mov_b32_e32 v190, v218
	v_mov_b32_e32 v191, v219
	v_mfma_scale_f32_16x16x128_f8f6f4 v[122:125], v[150:155], v[168:173], v[122:125], v196, v208 op_sel_hi:[0,0,0] cbsz:2 blgp:2
	v_mfma_scale_f32_16x16x128_f8f6f4 v[110:113], v[144:149], v[174:179], v[110:113], v192, v212 op_sel_hi:[0,0,0] cbsz:2 blgp:2
	v_mfma_scale_f32_16x16x128_f8f6f4 v[106:109], v[150:155], v[174:179], v[106:109], v196, v212 op_sel_hi:[0,0,0] cbsz:2 blgp:2
	v_mfma_scale_f32_16x16x128_f8f6f4 v[94:97], v[144:149], v[180:185], v[94:97], v192, v216 op_sel_hi:[0,0,0] cbsz:2 blgp:2
	v_mfma_scale_f32_16x16x128_f8f6f4 v[90:93], v[150:155], v[180:185], v[90:93], v196, v216 op_sel_hi:[0,0,0] cbsz:2 blgp:2
	v_mfma_scale_f32_16x16x128_f8f6f4 v[222:225], v[144:149], v[186:191], v[78:81], v192, v220 op_sel_hi:[0,0,0] cbsz:2 blgp:2
	v_mfma_scale_f32_16x16x128_f8f6f4 v[226:229], v[150:155], v[186:191], v[74:77], v196, v220 op_sel_hi:[0,0,0] cbsz:2 blgp:2
	v_mov_b32_e32 v160, v198
	v_mov_b32_e32 v161, v199
	v_mov_b32_e32 v166, v202
	v_mov_b32_e32 v167, v203
	v_mfma_scale_f32_16x16x128_f8f6f4 v[118:121], v[156:161], v[168:173], v[118:121], v200, v208 op_sel_hi:[0,0,0] cbsz:2 blgp:2
	s_nop 0
	v_mfma_scale_f32_16x16x128_f8f6f4 v[114:117], v[162:167], v[168:173], v[114:117], v204, v208 op_sel_hi:[0,0,0] cbsz:2 blgp:2
	v_mfma_scale_f32_16x16x128_f8f6f4 v[102:105], v[156:161], v[174:179], v[102:105], v200, v212 op_sel_hi:[0,0,0] cbsz:2 blgp:2
	v_mfma_scale_f32_16x16x128_f8f6f4 v[98:101], v[162:167], v[174:179], v[98:101], v204, v212 op_sel_hi:[0,0,0] cbsz:2 blgp:2
	v_mfma_scale_f32_16x16x128_f8f6f4 v[168:171], v[156:161], v[180:185], v[86:89], v200, v216 op_sel_hi:[0,0,0] cbsz:2 blgp:2
	v_mfma_scale_f32_16x16x128_f8f6f4 v[172:175], v[162:167], v[180:185], v[82:85], v204, v216 op_sel_hi:[0,0,0] cbsz:2 blgp:2
	v_mfma_scale_f32_16x16x128_f8f6f4 v[176:179], v[156:161], v[186:191], v[70:73], v200, v220 op_sel_hi:[0,0,0] cbsz:2 blgp:2
	v_mfma_scale_f32_16x16x128_f8f6f4 v[180:183], v[162:167], v[186:191], v[66:69], v204, v220 op_sel_hi:[0,0,0] cbsz:2 blgp:2
	s_barrier
	v_lshl_add_u64 v[138:139], s[48:49], 0, v[132:133]
	s_add_i32 s48, s58, s29
	s_mov_b32 m0, s48
	ds_read_b128 v[66:69], v142 offset:16384
	ds_read_b128 v[184:187], v142 offset:17408
	ds_read_b128 v[72:75], v142 offset:18432
	ds_read_b128 v[188:191], v142 offset:19456
	ds_read_b128 v[78:81], v142 offset:20480
	ds_read_b128 v[206:209], v142 offset:21504
	ds_read_b128 v[84:87], v142 offset:22528
	ds_read_b128 v[210:213], v142 offset:23552
	global_load_lds_dwordx4 v[138:139], off
	v_lshl_add_u64 v[70:71], v[138:139], 0, s[8:9]
	s_add_i32 m0, s48, 0x2000
	s_add_i32 s48, s59, s29
	global_load_lds_dwordx4 v[70:71], off
	v_lshl_add_u64 v[70:71], v[138:139], 0, s[10:11]
	s_mov_b32 m0, s48
	v_lshl_add_u64 v[246:247], s[46:47], 0, v[130:131]
	global_load_lds_dwordx4 v[70:71], off
	v_lshl_add_u64 v[70:71], v[138:139], 0, s[12:13]
	s_add_i32 m0, s48, 0x2000
	s_nop 0
	global_load_lds_dwordx4 v[70:71], off
	s_mov_b32 m0, s33
	v_lshl_add_u64 v[70:71], v[246:247], 0, s[8:9]
	global_load_lds_dwordx4 v[246:247], off
	s_mov_b32 m0, s40
	s_nop 0
	global_load_lds_dwordx4 v[70:71], off
	s_waitcnt vmcnt(8)
	s_waitcnt lgkmcnt(0)
	s_barrier
	s_waitcnt lgkmcnt(0)
	v_mov_b32_e32 v70, v184
	v_mov_b32_e32 v71, v185
	v_mov_b32_e32 v76, v188
	v_mov_b32_e32 v77, v189
	v_mfma_scale_f32_16x16x128_f8f6f4 v[62:65], v[144:149], v[66:71], v[62:65], v192, v186 op_sel_hi:[0,0,0] cbsz:2 blgp:2
	v_mov_b32_e32 v82, v206
	v_mov_b32_e32 v83, v207
	v_mov_b32_e32 v88, v210
	v_mfma_scale_f32_16x16x128_f8f6f4 v[58:61], v[150:155], v[66:71], v[58:61], v196, v186 op_sel_hi:[0,0,0] cbsz:2 blgp:2
	v_mov_b32_e32 v89, v211
	v_mfma_scale_f32_16x16x128_f8f6f4 v[46:49], v[144:149], v[72:77], v[46:49], v192, v190 op_sel_hi:[0,0,0] cbsz:2 blgp:2
	v_mfma_scale_f32_16x16x128_f8f6f4 v[42:45], v[150:155], v[72:77], v[42:45], v196, v190 op_sel_hi:[0,0,0] cbsz:2 blgp:2
	v_mfma_scale_f32_16x16x128_f8f6f4 v[214:217], v[144:149], v[78:83], v[30:33], v192, v208 op_sel_hi:[0,0,0] cbsz:2 blgp:2
	v_mfma_scale_f32_16x16x128_f8f6f4 v[218:221], v[150:155], v[78:83], v[26:29], v196, v208 op_sel_hi:[0,0,0] cbsz:2 blgp:2
	v_mfma_scale_f32_16x16x128_f8f6f4 v[192:195], v[144:149], v[84:89], v[14:17], v192, v212 op_sel_hi:[0,0,0] cbsz:2 blgp:2
	v_mfma_scale_f32_16x16x128_f8f6f4 v[196:199], v[150:155], v[84:89], v[10:13], v196, v212 op_sel_hi:[0,0,0] cbsz:2 blgp:2
	v_mfma_scale_f32_16x16x128_f8f6f4 v[54:57], v[156:161], v[66:71], v[54:57], v200, v186 op_sel_hi:[0,0,0] cbsz:2 blgp:2
	v_mfma_scale_f32_16x16x128_f8f6f4 v[50:53], v[162:167], v[66:71], v[50:53], v204, v186 op_sel_hi:[0,0,0] cbsz:2 blgp:2
	v_mfma_scale_f32_16x16x128_f8f6f4 v[38:41], v[156:161], v[72:77], v[38:41], v200, v190 op_sel_hi:[0,0,0] cbsz:2 blgp:2
	v_mfma_scale_f32_16x16x128_f8f6f4 v[184:187], v[162:167], v[72:77], v[34:37], v204, v190 op_sel_hi:[0,0,0] cbsz:2 blgp:2
	v_mfma_scale_f32_16x16x128_f8f6f4 v[188:191], v[156:161], v[78:83], v[22:25], v200, v208 op_sel_hi:[0,0,0] cbsz:2 blgp:2
	v_mfma_scale_f32_16x16x128_f8f6f4 v[206:209], v[162:167], v[78:83], v[18:21], v204, v208 op_sel_hi:[0,0,0] cbsz:2 blgp:2
	v_mfma_scale_f32_16x16x128_f8f6f4 v[200:203], v[156:161], v[84:89], v[6:9], v200, v212 op_sel_hi:[0,0,0] cbsz:2 blgp:2
	v_mfma_scale_f32_16x16x128_f8f6f4 v[210:213], v[162:167], v[84:89], v[2:5], v204, v212 op_sel_hi:[0,0,0] cbsz:2 blgp:2
	s_barrier
	s_add_i32 s46, 0, 0x18000
	v_add_u32_e32 v6, s46, v1
	s_add_i32 s47, 0, 0x1c000
	ds_read_b128 v[2:5], v6
	ds_read_b128 v[230:233], v6 offset:1024
	ds_read_b128 v[8:11], v6 offset:2048
	ds_read_b128 v[234:237], v6 offset:3072
	v_add_u32_e32 v6, s47, v1
	ds_read_b128 v[144:147], v6
	ds_read_b128 v[238:241], v6 offset:1024
	ds_read_b128 v[150:153], v6 offset:2048
	ds_read_b128 v[242:245], v6 offset:3072
	s_mov_b32 m0, s41
	v_lshl_add_u64 v[6:7], v[246:247], 0, s[10:11]
	ds_read_b128 v[14:17], v142 offset:32768
	ds_read_b128 v[66:69], v142 offset:33792
	ds_read_b128 v[20:23], v142 offset:34816
	ds_read_b128 v[70:73], v142 offset:35840
	ds_read_b128 v[26:29], v142 offset:36864
	ds_read_b128 v[80:83], v142 offset:37888
	ds_read_b128 v[32:35], v142 offset:38912
	ds_read_b128 v[154:157], v142 offset:39936
	global_load_lds_dwordx4 v[6:7], off
	v_lshl_add_u64 v[6:7], v[246:247], 0, s[12:13]
	s_mov_b32 m0, s42
	s_nop 0
	global_load_lds_dwordx4 v[6:7], off
	s_waitcnt vmcnt(8)
	s_waitcnt lgkmcnt(0)
	s_barrier
	s_waitcnt lgkmcnt(0)
	v_mov_b32_e32 v6, v230
	v_mov_b32_e32 v7, v231
	v_mov_b32_e32 v12, v234
	v_mov_b32_e32 v13, v235
	v_mov_b32_e32 v18, v66
	v_mov_b32_e32 v19, v67
	v_mov_b32_e32 v24, v70
	v_mov_b32_e32 v25, v71
	v_mov_b32_e32 v30, v80
	v_mov_b32_e32 v31, v81
	v_mov_b32_e32 v36, v154
	v_mov_b32_e32 v37, v155
	v_mfma_scale_f32_16x16x128_f8f6f4 v[126:129], v[2:7], v[14:19], v[126:129], v232, v68 op_sel_hi:[0,0,0] cbsz:2 blgp:2
	v_mfma_scale_f32_16x16x128_f8f6f4 v[122:125], v[8:13], v[14:19], v[122:125], v236, v68 op_sel_hi:[0,0,0] cbsz:2 blgp:2
	v_mfma_scale_f32_16x16x128_f8f6f4 v[110:113], v[2:7], v[20:25], v[110:113], v232, v72 op_sel_hi:[0,0,0] cbsz:2 blgp:2
	v_mfma_scale_f32_16x16x128_f8f6f4 v[106:109], v[8:13], v[20:25], v[106:109], v236, v72 op_sel_hi:[0,0,0] cbsz:2 blgp:2
	v_mfma_scale_f32_16x16x128_f8f6f4 v[94:97], v[2:7], v[26:31], v[94:97], v232, v82 op_sel_hi:[0,0,0] cbsz:2 blgp:2
	v_mfma_scale_f32_16x16x128_f8f6f4 v[90:93], v[8:13], v[26:31], v[90:93], v236, v82 op_sel_hi:[0,0,0] cbsz:2 blgp:2
	v_mfma_scale_f32_16x16x128_f8f6f4 v[78:81], v[2:7], v[32:37], v[222:225], v232, v156 op_sel_hi:[0,0,0] cbsz:2 blgp:2
	v_mfma_scale_f32_16x16x128_f8f6f4 v[74:77], v[8:13], v[32:37], v[226:229], v236, v156 op_sel_hi:[0,0,0] cbsz:2 blgp:2
	v_mov_b32_e32 v148, v238
	v_mov_b32_e32 v149, v239
	v_mov_b32_e32 v154, v242
	v_mov_b32_e32 v155, v243
	v_mfma_scale_f32_16x16x128_f8f6f4 v[118:121], v[144:149], v[14:19], v[118:121], v240, v68 op_sel_hi:[0,0,0] cbsz:2 blgp:2
	s_nop 0
	v_mfma_scale_f32_16x16x128_f8f6f4 v[114:117], v[150:155], v[14:19], v[114:117], v244, v68 op_sel_hi:[0,0,0] cbsz:2 blgp:2
	v_mfma_scale_f32_16x16x128_f8f6f4 v[102:105], v[144:149], v[20:25], v[102:105], v240, v72 op_sel_hi:[0,0,0] cbsz:2 blgp:2
	v_mfma_scale_f32_16x16x128_f8f6f4 v[98:101], v[150:155], v[20:25], v[98:101], v244, v72 op_sel_hi:[0,0,0] cbsz:2 blgp:2
	v_mfma_scale_f32_16x16x128_f8f6f4 v[86:89], v[144:149], v[26:31], v[168:171], v240, v82 op_sel_hi:[0,0,0] cbsz:2 blgp:2
	v_mfma_scale_f32_16x16x128_f8f6f4 v[82:85], v[150:155], v[26:31], v[172:175], v244, v82 op_sel_hi:[0,0,0] cbsz:2 blgp:2
	v_mfma_scale_f32_16x16x128_f8f6f4 v[70:73], v[144:149], v[32:37], v[176:179], v240, v156 op_sel_hi:[0,0,0] cbsz:2 blgp:2
	v_mfma_scale_f32_16x16x128_f8f6f4 v[66:69], v[150:155], v[32:37], v[180:183], v244, v156 op_sel_hi:[0,0,0] cbsz:2 blgp:2
	s_barrier
	s_add_i32 s46, s46, s29
	v_lshl_add_u64 v[14:15], v[138:139], 0, s[24:25]
	s_mov_b32 m0, s46
	ds_read_b128 v[18:21], v142 offset:49152
	ds_read_b128 v[22:25], v142 offset:50176
	ds_read_b128 v[156:159], v142 offset:51200
	ds_read_b128 v[32:35], v142 offset:52224
	ds_read_b128 v[162:165], v142 offset:53248
	ds_read_b128 v[172:175], v142 offset:54272
	ds_read_b128 v[168:171], v142 offset:55296
	ds_read_b128 v[176:179], v142 offset:56320
	global_load_lds_dwordx4 v[14:15], off
	v_lshl_add_u64 v[14:15], v[138:139], 0, s[26:27]
	s_add_i32 m0, s46, 0x2000
	s_add_i32 s46, s47, s29
	global_load_lds_dwordx4 v[14:15], off
	v_lshl_add_u64 v[14:15], v[138:139], 0, s[30:31]
	s_mov_b32 m0, s46
	s_nop 0
	global_load_lds_dwordx4 v[14:15], off
	v_lshl_add_u64 v[14:15], v[138:139], 0, s[34:35]
	s_add_i32 m0, s46, 0x2000
	s_nop 0
	global_load_lds_dwordx4 v[14:15], off
	v_lshl_add_u64 v[14:15], v[246:247], 0, s[24:25]
	s_mov_b32 m0, s51
	s_nop 0
	global_load_lds_dwordx4 v[14:15], off
	v_lshl_add_u64 v[14:15], v[246:247], 0, s[26:27]
	s_mov_b32 m0, s52
	s_nop 0
	global_load_lds_dwordx4 v[14:15], off
	s_waitcnt vmcnt(8)
	s_waitcnt lgkmcnt(0)
	s_barrier
	s_waitcnt lgkmcnt(0)
	v_mov_b32_e32 v160, v32
	v_mov_b32_e32 v161, v33
	v_mov_b32_e32 v166, v172
	v_mov_b32_e32 v167, v173
	v_mov_b32_e32 v172, v176
	v_mov_b32_e32 v173, v177
	v_mfma_scale_f32_16x16x128_f8f6f4 v[62:65], v[2:7], v[18:23], v[62:65], v232, v24 op_sel_hi:[0,0,0] cbsz:2 blgp:2
	v_mfma_scale_f32_16x16x128_f8f6f4 v[58:61], v[8:13], v[18:23], v[58:61], v236, v24 op_sel_hi:[0,0,0] cbsz:2 blgp:2
	v_mfma_scale_f32_16x16x128_f8f6f4 v[46:49], v[2:7], v[156:161], v[46:49], v232, v34 op_sel_hi:[0,0,0] cbsz:2 blgp:2
	v_mfma_scale_f32_16x16x128_f8f6f4 v[42:45], v[8:13], v[156:161], v[42:45], v236, v34 op_sel_hi:[0,0,0] cbsz:2 blgp:2
	v_mfma_scale_f32_16x16x128_f8f6f4 v[30:33], v[2:7], v[162:167], v[214:217], v232, v174 op_sel_hi:[0,0,0] cbsz:2 blgp:2
	v_mfma_scale_f32_16x16x128_f8f6f4 v[26:29], v[8:13], v[162:167], v[218:221], v236, v174 op_sel_hi:[0,0,0] cbsz:2 blgp:2
	v_mfma_scale_f32_16x16x128_f8f6f4 v[14:17], v[2:7], v[168:173], v[192:195], v232, v178 op_sel_hi:[0,0,0] cbsz:2 blgp:2
	v_mfma_scale_f32_16x16x128_f8f6f4 v[10:13], v[8:13], v[168:173], v[196:199], v236, v178 op_sel_hi:[0,0,0] cbsz:2 blgp:2
	v_mfma_scale_f32_16x16x128_f8f6f4 v[54:57], v[144:149], v[18:23], v[54:57], v240, v24 op_sel_hi:[0,0,0] cbsz:2 blgp:2
	v_mfma_scale_f32_16x16x128_f8f6f4 v[50:53], v[150:155], v[18:23], v[50:53], v244, v24 op_sel_hi:[0,0,0] cbsz:2 blgp:2
	v_mfma_scale_f32_16x16x128_f8f6f4 v[38:41], v[144:149], v[156:161], v[38:41], v240, v34 op_sel_hi:[0,0,0] cbsz:2 blgp:2
	v_mfma_scale_f32_16x16x128_f8f6f4 v[34:37], v[150:155], v[156:161], v[184:187], v244, v34 op_sel_hi:[0,0,0] cbsz:2 blgp:2
	v_mfma_scale_f32_16x16x128_f8f6f4 v[22:25], v[144:149], v[162:167], v[188:191], v240, v174 op_sel_hi:[0,0,0] cbsz:2 blgp:2
	v_mfma_scale_f32_16x16x128_f8f6f4 v[18:21], v[150:155], v[162:167], v[206:209], v244, v174 op_sel_hi:[0,0,0] cbsz:2 blgp:2
	v_mfma_scale_f32_16x16x128_f8f6f4 v[6:9], v[144:149], v[168:173], v[200:203], v240, v178 op_sel_hi:[0,0,0] cbsz:2 blgp:2
	v_mfma_scale_f32_16x16x128_f8f6f4 v[2:5], v[150:155], v[168:173], v[210:213], v244, v178 op_sel_hi:[0,0,0] cbsz:2 blgp:2
	s_barrier
	s_add_u32 s44, s44, 0x100
	s_addc_u32 s45, s45, 0
	s_add_u32 s5, s5, 0x100
	s_addc_u32 s67, s67, 0
	s_cmp_ge_i32 s76, s66
	s_mov_b32 s46, s76
	s_cbranch_scc0 .LBB0_2291
	s_setprio 0
	v_readlane_b32 s76, v254, 6
	v_readlane_b32 s77, v254, 7
	v_readlane_b32 s78, v254, 8
	v_readlane_b32 s79, v254, 9
	v_readlane_b32 s80, v254, 10
	v_readlane_b32 s81, v254, 11
	v_readlane_b32 s82, v254, 12
	v_readlane_b32 s83, v254, 13
	s_and_b64 vcc, exec, s[36:37]
	s_cbranch_vccz .LBB0_2294
